# o30 without the nt hint on the f32 weight loads of the GU1/GU2 idle-tail converters
# baseline (speedup 1.0000x reference)
.Lw1d_loop:
	v_readfirstlane_b32 s98, v18
	s_nop 3
	s_cmpk_ge_u32 s98, 0x780
	s_cbranch_scc1 .Lw1d_done
	s_cmpk_ge_u32 s98, 0x580
	s_cbranch_scc1 .Lwo_item
	s_lshr_b32 s99, s98, 4
	s_and_b32 s100, s98, 15
	s_lshl_b32 s101, s99, 19
	s_lshl_b32 s0, s100, 9
	s_add_u32 s0, s0, s101
	s_add_u32 s0, s8, s0
	s_addc_u32 s1, s9, 0
	s_mul_i32 s2, s100, 0x160000
	s_lshl_b32 s3, s99, 7
	s_add_u32 s2, s2, s3
	s_add_u32 s2, s2, 0x2d60200
	s_add_u32 s2, s86, s2
	s_addc_u32 s3, s87, 0
	s_add_u32 s4, s2, 0xb0000
	s_addc_u32 s5, s3, 0
	global_load_dwordx4 v[154:157], v8, s[0:1]
	global_load_dwordx4 v[204:207], v8, s[0:1] offset:256
	s_add_u32 s0, s0, 0x2000
	s_addc_u32 s1, s1, 0
	global_load_dwordx4 v[158:161], v8, s[0:1]
	global_load_dwordx4 v[208:211], v8, s[0:1] offset:256
	s_add_u32 s0, s0, 0x2000
	s_addc_u32 s1, s1, 0
	global_load_dwordx4 v[162:165], v8, s[0:1]
	global_load_dwordx4 v[212:215], v8, s[0:1] offset:256
	s_add_u32 s0, s0, 0x2000
	s_addc_u32 s1, s1, 0
	global_load_dwordx4 v[166:169], v8, s[0:1]
	global_load_dwordx4 v[216:219], v8, s[0:1] offset:256
	s_add_u32 s0, s0, 0x2000
	s_addc_u32 s1, s1, 0
	global_load_dwordx4 v[170:173], v8, s[0:1]
	global_load_dwordx4 v[220:223], v8, s[0:1] offset:256
	s_add_u32 s0, s0, 0x2000
	s_addc_u32 s1, s1, 0
	global_load_dwordx4 v[174:177], v8, s[0:1]
	global_load_dwordx4 v[224:227], v8, s[0:1] offset:256
	s_add_u32 s0, s0, 0x2000
	s_addc_u32 s1, s1, 0
	global_load_dwordx4 v[178:181], v8, s[0:1]
	global_load_dwordx4 v[228:231], v8, s[0:1] offset:256
	s_add_u32 s0, s0, 0x2000
	s_addc_u32 s1, s1, 0
	global_load_dwordx4 v[182:185], v8, s[0:1]
	global_load_dwordx4 v[232:235], v8, s[0:1] offset:256
	s_add_u32 s0, s0, 0x2000
	s_addc_u32 s1, s1, 0
	global_load_dwordx4 v[186:189], v8, s[0:1]
	global_load_dwordx4 v[236:239], v8, s[0:1] offset:256
	s_add_u32 s0, s0, 0x2000
	s_addc_u32 s1, s1, 0
	global_load_dwordx4 v[190:193], v8, s[0:1]
	global_load_dwordx4 v[240:243], v8, s[0:1] offset:256
	s_add_u32 s0, s0, 0x2000
	s_addc_u32 s1, s1, 0
	global_load_dwordx4 v[194:197], v8, s[0:1]
	global_load_dwordx4 v[244:247], v8, s[0:1] offset:256
	s_add_u32 s0, s0, 0x2000
	s_addc_u32 s1, s1, 0
	global_load_dwordx4 v[198:201], v8, s[0:1]
	global_load_dwordx4 v[248:251], v8, s[0:1] offset:256
	s_add_u32 s0, s0, 0x2000
	s_addc_u32 s1, s1, 0
	global_load_dwordx4 v[130:133], v8, s[0:1]
	global_load_dwordx4 v[50:53], v8, s[0:1] offset:256
	s_add_u32 s0, s0, 0x2000
	s_addc_u32 s1, s1, 0
	global_load_dwordx4 v[134:137], v8, s[0:1]
	global_load_dwordx4 v[54:57], v8, s[0:1] offset:256
	s_add_u32 s0, s0, 0x2000
	s_addc_u32 s1, s1, 0
	global_load_dwordx4 v[138:141], v8, s[0:1]
	global_load_dwordx4 v[58:61], v8, s[0:1] offset:256
	s_add_u32 s0, s0, 0x2000
	s_addc_u32 s1, s1, 0
	global_load_dwordx4 v[142:145], v8, s[0:1]
	global_load_dwordx4 v[62:65], v8, s[0:1] offset:256
	s_mov_b64 exec, 1
	global_atomic_add v18, v16, v17, s[6:7] sc0
	s_mov_b64 exec, -1
	s_waitcnt vmcnt(1)
	v_cvt_pk_bf16_f32 v20, v154, v158
	v_cvt_pk_bf16_f32 v21, v162, v166
	v_cvt_pk_bf16_f32 v22, v170, v174
	v_cvt_pk_bf16_f32 v23, v178, v182
	global_store_dwordx4 v12, v[20:23], s[2:3]
	v_cvt_pk_bf16_f32 v24, v186, v190
	v_cvt_pk_bf16_f32 v25, v194, v198
	v_cvt_pk_bf16_f32 v26, v130, v134
	v_cvt_pk_bf16_f32 v27, v138, v142
	global_store_dwordx4 v12, v[24:27], s[2:3] offset:16
	v_cvt_pk_bf16_f32 v28, v155, v159
	v_cvt_pk_bf16_f32 v29, v163, v167
	v_cvt_pk_bf16_f32 v30, v171, v175
	v_cvt_pk_bf16_f32 v31, v179, v183
	global_store_dwordx4 v13, v[28:31], s[2:3]
	v_cvt_pk_bf16_f32 v32, v187, v191
	v_cvt_pk_bf16_f32 v33, v195, v199
	v_cvt_pk_bf16_f32 v34, v131, v135
	v_cvt_pk_bf16_f32 v35, v139, v143
	global_store_dwordx4 v13, v[32:35], s[2:3] offset:16
	v_cvt_pk_bf16_f32 v36, v156, v160
	v_cvt_pk_bf16_f32 v37, v164, v168
	v_cvt_pk_bf16_f32 v38, v172, v176
	v_cvt_pk_bf16_f32 v39, v180, v184
	global_store_dwordx4 v14, v[36:39], s[2:3]
	v_cvt_pk_bf16_f32 v40, v188, v192
	v_cvt_pk_bf16_f32 v41, v196, v200
	v_cvt_pk_bf16_f32 v42, v132, v136
	v_cvt_pk_bf16_f32 v43, v140, v144
	global_store_dwordx4 v14, v[40:43], s[2:3] offset:16
	v_cvt_pk_bf16_f32 v20, v157, v161
	v_cvt_pk_bf16_f32 v21, v165, v169
	v_cvt_pk_bf16_f32 v22, v173, v177
	v_cvt_pk_bf16_f32 v23, v181, v185
	global_store_dwordx4 v15, v[20:23], s[2:3]
	v_cvt_pk_bf16_f32 v24, v189, v193
	v_cvt_pk_bf16_f32 v25, v197, v201
	v_cvt_pk_bf16_f32 v26, v133, v137
	v_cvt_pk_bf16_f32 v27, v141, v145
	global_store_dwordx4 v15, v[24:27], s[2:3] offset:16
	v_cvt_pk_bf16_f32 v28, v204, v208
	v_cvt_pk_bf16_f32 v29, v212, v216
	v_cvt_pk_bf16_f32 v30, v220, v224
	v_cvt_pk_bf16_f32 v31, v228, v232
	global_store_dwordx4 v12, v[28:31], s[4:5]
	v_cvt_pk_bf16_f32 v32, v236, v240
	v_cvt_pk_bf16_f32 v33, v244, v248
	v_cvt_pk_bf16_f32 v34, v50, v54
	v_cvt_pk_bf16_f32 v35, v58, v62
	global_store_dwordx4 v12, v[32:35], s[4:5] offset:16
	v_cvt_pk_bf16_f32 v36, v205, v209
	v_cvt_pk_bf16_f32 v37, v213, v217
	v_cvt_pk_bf16_f32 v38, v221, v225
	v_cvt_pk_bf16_f32 v39, v229, v233
	global_store_dwordx4 v13, v[36:39], s[4:5]
	v_cvt_pk_bf16_f32 v40, v237, v241
	v_cvt_pk_bf16_f32 v41, v245, v249
	v_cvt_pk_bf16_f32 v42, v51, v55
	v_cvt_pk_bf16_f32 v43, v59, v63
	global_store_dwordx4 v13, v[40:43], s[4:5] offset:16
	v_cvt_pk_bf16_f32 v20, v206, v210
	v_cvt_pk_bf16_f32 v21, v214, v218
	v_cvt_pk_bf16_f32 v22, v222, v226
	v_cvt_pk_bf16_f32 v23, v230, v234
	global_store_dwordx4 v14, v[20:23], s[4:5]
	v_cvt_pk_bf16_f32 v24, v238, v242
	v_cvt_pk_bf16_f32 v25, v246, v250
	v_cvt_pk_bf16_f32 v26, v52, v56
	v_cvt_pk_bf16_f32 v27, v60, v64
	global_store_dwordx4 v14, v[24:27], s[4:5] offset:16
	v_cvt_pk_bf16_f32 v28, v207, v211
	v_cvt_pk_bf16_f32 v29, v215, v219
	v_cvt_pk_bf16_f32 v30, v223, v227
	v_cvt_pk_bf16_f32 v31, v231, v235
	global_store_dwordx4 v15, v[28:31], s[4:5]
	v_cvt_pk_bf16_f32 v32, v239, v243
	v_cvt_pk_bf16_f32 v33, v247, v251
	v_cvt_pk_bf16_f32 v34, v53, v57
	v_cvt_pk_bf16_f32 v35, v61, v65
	global_store_dwordx4 v15, v[32:35], s[4:5] offset:16
	s_waitcnt vmcnt(16)
	s_branch .Lw1d_loop
.Lwo_item:
	s_sub_u32 s98, s98, 0x580
	s_lshr_b32 s99, s98, 4
	s_and_b32 s100, s98, 15
	s_lshl_b32 s101, s99, 19
	s_lshl_b32 s0, s100, 9
	s_add_u32 s0, s0, s101
	s_add_u32 s0, s10, s0
	s_addc_u32 s1, s11, 0
	s_lshl_b32 s2, s100, 19
	s_lshl_b32 s3, s99, 7
	s_add_u32 s2, s2, s3
	s_add_u32 s2, s2, 0x8460200
	s_add_u32 s2, s86, s2
	s_addc_u32 s3, s87, 0
	s_add_u32 s4, s2, 0x40000
	s_addc_u32 s5, s3, 0
	global_load_dwordx4 v[154:157], v8, s[0:1]
	global_load_dwordx4 v[204:207], v8, s[0:1] offset:256
	s_add_u32 s0, s0, 0x2000
	s_addc_u32 s1, s1, 0
	global_load_dwordx4 v[158:161], v8, s[0:1]
	global_load_dwordx4 v[208:211], v8, s[0:1] offset:256
	s_add_u32 s0, s0, 0x2000
	s_addc_u32 s1, s1, 0
	global_load_dwordx4 v[162:165], v8, s[0:1]
	global_load_dwordx4 v[212:215], v8, s[0:1] offset:256
	s_add_u32 s0, s0, 0x2000
	s_addc_u32 s1, s1, 0
	global_load_dwordx4 v[166:169], v8, s[0:1]
	global_load_dwordx4 v[216:219], v8, s[0:1] offset:256
	s_add_u32 s0, s0, 0x2000
	s_addc_u32 s1, s1, 0
	global_load_dwordx4 v[170:173], v8, s[0:1]
	global_load_dwordx4 v[220:223], v8, s[0:1] offset:256
	s_add_u32 s0, s0, 0x2000
	s_addc_u32 s1, s1, 0
	global_load_dwordx4 v[174:177], v8, s[0:1]
	global_load_dwordx4 v[224:227], v8, s[0:1] offset:256
	s_add_u32 s0, s0, 0x2000
	s_addc_u32 s1, s1, 0
	global_load_dwordx4 v[178:181], v8, s[0:1]
	global_load_dwordx4 v[228:231], v8, s[0:1] offset:256
	s_add_u32 s0, s0, 0x2000
	s_addc_u32 s1, s1, 0
	global_load_dwordx4 v[182:185], v8, s[0:1]
	global_load_dwordx4 v[232:235], v8, s[0:1] offset:256
	s_add_u32 s0, s0, 0x2000
	s_addc_u32 s1, s1, 0
	global_load_dwordx4 v[186:189], v8, s[0:1]
	global_load_dwordx4 v[236:239], v8, s[0:1] offset:256
	s_add_u32 s0, s0, 0x2000
	s_addc_u32 s1, s1, 0
	global_load_dwordx4 v[190:193], v8, s[0:1]
	global_load_dwordx4 v[240:243], v8, s[0:1] offset:256
	s_add_u32 s0, s0, 0x2000
	s_addc_u32 s1, s1, 0
	global_load_dwordx4 v[194:197], v8, s[0:1]
	global_load_dwordx4 v[244:247], v8, s[0:1] offset:256
	s_add_u32 s0, s0, 0x2000
	s_addc_u32 s1, s1, 0
	global_load_dwordx4 v[198:201], v8, s[0:1]
	global_load_dwordx4 v[248:251], v8, s[0:1] offset:256
	s_add_u32 s0, s0, 0x2000
	s_addc_u32 s1, s1, 0
	global_load_dwordx4 v[130:133], v8, s[0:1]
	global_load_dwordx4 v[50:53], v8, s[0:1] offset:256
	s_add_u32 s0, s0, 0x2000
	s_addc_u32 s1, s1, 0
	global_load_dwordx4 v[134:137], v8, s[0:1]
	global_load_dwordx4 v[54:57], v8, s[0:1] offset:256
	s_add_u32 s0, s0, 0x2000
	s_addc_u32 s1, s1, 0
	global_load_dwordx4 v[138:141], v8, s[0:1]
	global_load_dwordx4 v[58:61], v8, s[0:1] offset:256
	s_add_u32 s0, s0, 0x2000
	s_addc_u32 s1, s1, 0
	global_load_dwordx4 v[142:145], v8, s[0:1]
	global_load_dwordx4 v[62:65], v8, s[0:1] offset:256
	s_mov_b64 exec, 1
	global_atomic_add v18, v16, v17, s[6:7] sc0
	s_mov_b64 exec, -1
	s_waitcnt vmcnt(1)
	v_cvt_pk_bf16_f32 v20, v154, v158
	v_cvt_pk_bf16_f32 v21, v162, v166
	v_cvt_pk_bf16_f32 v22, v170, v174
	v_cvt_pk_bf16_f32 v23, v178, v182
	global_store_dwordx4 v44, v[20:23], s[2:3]
	v_cvt_pk_bf16_f32 v24, v186, v190
	v_cvt_pk_bf16_f32 v25, v194, v198
	v_cvt_pk_bf16_f32 v26, v130, v134
	v_cvt_pk_bf16_f32 v27, v138, v142
	global_store_dwordx4 v44, v[24:27], s[2:3] offset:16
	v_cvt_pk_bf16_f32 v28, v155, v159
	v_cvt_pk_bf16_f32 v29, v163, v167
	v_cvt_pk_bf16_f32 v30, v171, v175
	v_cvt_pk_bf16_f32 v31, v179, v183
	global_store_dwordx4 v45, v[28:31], s[2:3]
	v_cvt_pk_bf16_f32 v32, v187, v191
	v_cvt_pk_bf16_f32 v33, v195, v199
	v_cvt_pk_bf16_f32 v34, v131, v135
	v_cvt_pk_bf16_f32 v35, v139, v143
	global_store_dwordx4 v45, v[32:35], s[2:3] offset:16
	v_cvt_pk_bf16_f32 v36, v156, v160
	v_cvt_pk_bf16_f32 v37, v164, v168
	v_cvt_pk_bf16_f32 v38, v172, v176
	v_cvt_pk_bf16_f32 v39, v180, v184
	global_store_dwordx4 v46, v[36:39], s[2:3]
	v_cvt_pk_bf16_f32 v40, v188, v192
	v_cvt_pk_bf16_f32 v41, v196, v200
	v_cvt_pk_bf16_f32 v42, v132, v136
	v_cvt_pk_bf16_f32 v43, v140, v144
	global_store_dwordx4 v46, v[40:43], s[2:3] offset:16
	v_cvt_pk_bf16_f32 v20, v157, v161
	v_cvt_pk_bf16_f32 v21, v165, v169
	v_cvt_pk_bf16_f32 v22, v173, v177
	v_cvt_pk_bf16_f32 v23, v181, v185
	global_store_dwordx4 v47, v[20:23], s[2:3]
	v_cvt_pk_bf16_f32 v24, v189, v193
	v_cvt_pk_bf16_f32 v25, v197, v201
	v_cvt_pk_bf16_f32 v26, v133, v137
	v_cvt_pk_bf16_f32 v27, v141, v145
	global_store_dwordx4 v47, v[24:27], s[2:3] offset:16
	v_cvt_pk_bf16_f32 v28, v204, v208
	v_cvt_pk_bf16_f32 v29, v212, v216
	v_cvt_pk_bf16_f32 v30, v220, v224
	v_cvt_pk_bf16_f32 v31, v228, v232
	global_store_dwordx4 v44, v[28:31], s[4:5]
	v_cvt_pk_bf16_f32 v32, v236, v240
	v_cvt_pk_bf16_f32 v33, v244, v248
	v_cvt_pk_bf16_f32 v34, v50, v54
	v_cvt_pk_bf16_f32 v35, v58, v62
	global_store_dwordx4 v44, v[32:35], s[4:5] offset:16
	v_cvt_pk_bf16_f32 v36, v205, v209
	v_cvt_pk_bf16_f32 v37, v213, v217
	v_cvt_pk_bf16_f32 v38, v221, v225
	v_cvt_pk_bf16_f32 v39, v229, v233
	global_store_dwordx4 v45, v[36:39], s[4:5]
	v_cvt_pk_bf16_f32 v40, v237, v241
	v_cvt_pk_bf16_f32 v41, v245, v249
	v_cvt_pk_bf16_f32 v42, v51, v55
	v_cvt_pk_bf16_f32 v43, v59, v63
	global_store_dwordx4 v45, v[40:43], s[4:5] offset:16
	v_cvt_pk_bf16_f32 v20, v206, v210
	v_cvt_pk_bf16_f32 v21, v214, v218
	v_cvt_pk_bf16_f32 v22, v222, v226
	v_cvt_pk_bf16_f32 v23, v230, v234
	global_store_dwordx4 v46, v[20:23], s[4:5]
	v_cvt_pk_bf16_f32 v24, v238, v242
	v_cvt_pk_bf16_f32 v25, v246, v250
	v_cvt_pk_bf16_f32 v26, v52, v56
	v_cvt_pk_bf16_f32 v27, v60, v64
	global_store_dwordx4 v46, v[24:27], s[4:5] offset:16
	v_cvt_pk_bf16_f32 v28, v207, v211
	v_cvt_pk_bf16_f32 v29, v215, v219
	v_cvt_pk_bf16_f32 v30, v223, v227
	v_cvt_pk_bf16_f32 v31, v231, v235
	global_store_dwordx4 v47, v[28:31], s[4:5]
	v_cvt_pk_bf16_f32 v32, v239, v243
	v_cvt_pk_bf16_f32 v33, v247, v251
	v_cvt_pk_bf16_f32 v34, v53, v57
	v_cvt_pk_bf16_f32 v35, v61, v65
	global_store_dwordx4 v47, v[32:35], s[4:5] offset:16
	s_waitcnt vmcnt(16)
	s_branch .Lw1d_loop

.Lw2d_loop:
	v_readfirstlane_b32 s98, v18
	s_nop 3
	s_cmpk_ge_u32 s98, 0x580
	s_cbranch_scc1 .Lw2d_done
	s_lshr_b32 s99, s98, 4
	s_and_b32 s100, s98, 15
	s_lshl_b32 s101, s99, 19
	s_lshl_b32 s0, s100, 9
	s_add_u32 s0, s0, s101
	s_add_u32 s0, s10, s0
	s_addc_u32 s1, s11, 0
	s_mul_i32 s2, s100, 0x160000
	s_lshl_b32 s3, s99, 7
	s_add_u32 s2, s2, s3
	s_add_u32 s2, s2, 0xb860200
	s_add_u32 s2, s86, s2
	s_addc_u32 s3, s87, 0
	s_add_u32 s6, s2, 0xb0000
	s_addc_u32 s7, s3, 0
	global_load_dwordx4 v[154:157], v8, s[0:1]
	global_load_dwordx4 v[204:207], v8, s[0:1] offset:256
	s_add_u32 s0, s0, 0x2000
	s_addc_u32 s1, s1, 0
	global_load_dwordx4 v[158:161], v8, s[0:1]
	global_load_dwordx4 v[208:211], v8, s[0:1] offset:256
	s_add_u32 s0, s0, 0x2000
	s_addc_u32 s1, s1, 0
	global_load_dwordx4 v[162:165], v8, s[0:1]
	global_load_dwordx4 v[212:215], v8, s[0:1] offset:256
	s_add_u32 s0, s0, 0x2000
	s_addc_u32 s1, s1, 0
	global_load_dwordx4 v[166:169], v8, s[0:1]
	global_load_dwordx4 v[216:219], v8, s[0:1] offset:256
	s_add_u32 s0, s0, 0x2000
	s_addc_u32 s1, s1, 0
	global_load_dwordx4 v[170:173], v8, s[0:1]
	global_load_dwordx4 v[220:223], v8, s[0:1] offset:256
	s_add_u32 s0, s0, 0x2000
	s_addc_u32 s1, s1, 0
	global_load_dwordx4 v[174:177], v8, s[0:1]
	global_load_dwordx4 v[224:227], v8, s[0:1] offset:256
	s_add_u32 s0, s0, 0x2000
	s_addc_u32 s1, s1, 0
	global_load_dwordx4 v[178:181], v8, s[0:1]
	global_load_dwordx4 v[228:231], v8, s[0:1] offset:256
	s_add_u32 s0, s0, 0x2000
	s_addc_u32 s1, s1, 0
	global_load_dwordx4 v[182:185], v8, s[0:1]
	global_load_dwordx4 v[232:235], v8, s[0:1] offset:256
	s_add_u32 s0, s0, 0x2000
	s_addc_u32 s1, s1, 0
	global_load_dwordx4 v[186:189], v8, s[0:1]
	global_load_dwordx4 v[236:239], v8, s[0:1] offset:256
	s_add_u32 s0, s0, 0x2000
	s_addc_u32 s1, s1, 0
	global_load_dwordx4 v[190:193], v8, s[0:1]
	global_load_dwordx4 v[240:243], v8, s[0:1] offset:256
	s_add_u32 s0, s0, 0x2000
	s_addc_u32 s1, s1, 0
	global_load_dwordx4 v[194:197], v8, s[0:1]
	global_load_dwordx4 v[244:247], v8, s[0:1] offset:256
	s_add_u32 s0, s0, 0x2000
	s_addc_u32 s1, s1, 0
	global_load_dwordx4 v[198:201], v8, s[0:1]
	global_load_dwordx4 v[248:251], v8, s[0:1] offset:256
	s_add_u32 s0, s0, 0x2000
	s_addc_u32 s1, s1, 0
	global_load_dwordx4 v[130:133], v8, s[0:1]
	global_load_dwordx4 v[50:53], v8, s[0:1] offset:256
	s_add_u32 s0, s0, 0x2000
	s_addc_u32 s1, s1, 0
	global_load_dwordx4 v[134:137], v8, s[0:1]
	global_load_dwordx4 v[54:57], v8, s[0:1] offset:256
	s_add_u32 s0, s0, 0x2000
	s_addc_u32 s1, s1, 0
	global_load_dwordx4 v[138:141], v8, s[0:1]
	global_load_dwordx4 v[58:61], v8, s[0:1] offset:256
	s_add_u32 s0, s0, 0x2000
	s_addc_u32 s1, s1, 0
	global_load_dwordx4 v[142:145], v8, s[0:1]
	global_load_dwordx4 v[62:65], v8, s[0:1] offset:256
	s_mov_b64 exec, 1
	global_atomic_add v18, v16, v17, s[8:9] sc0
	s_mov_b64 exec, -1
	s_waitcnt vmcnt(1)
	v_cvt_pk_bf16_f32 v20, v154, v158
	v_cvt_pk_bf16_f32 v21, v162, v166
	v_cvt_pk_bf16_f32 v22, v170, v174
	v_cvt_pk_bf16_f32 v23, v178, v182
	global_store_dwordx4 v12, v[20:23], s[2:3]
	v_cvt_pk_bf16_f32 v24, v186, v190
	v_cvt_pk_bf16_f32 v25, v194, v198
	v_cvt_pk_bf16_f32 v26, v130, v134
	v_cvt_pk_bf16_f32 v27, v138, v142
	global_store_dwordx4 v12, v[24:27], s[2:3] offset:16
	v_cvt_pk_bf16_f32 v28, v155, v159
	v_cvt_pk_bf16_f32 v29, v163, v167
	v_cvt_pk_bf16_f32 v30, v171, v175
	v_cvt_pk_bf16_f32 v31, v179, v183
	global_store_dwordx4 v13, v[28:31], s[2:3]
	v_cvt_pk_bf16_f32 v32, v187, v191
	v_cvt_pk_bf16_f32 v33, v195, v199
	v_cvt_pk_bf16_f32 v34, v131, v135
	v_cvt_pk_bf16_f32 v35, v139, v143
	global_store_dwordx4 v13, v[32:35], s[2:3] offset:16
	v_cvt_pk_bf16_f32 v36, v156, v160
	v_cvt_pk_bf16_f32 v37, v164, v168
	v_cvt_pk_bf16_f32 v38, v172, v176
	v_cvt_pk_bf16_f32 v39, v180, v184
	global_store_dwordx4 v14, v[36:39], s[2:3]
	v_cvt_pk_bf16_f32 v40, v188, v192
	v_cvt_pk_bf16_f32 v41, v196, v200
	v_cvt_pk_bf16_f32 v42, v132, v136
	v_cvt_pk_bf16_f32 v43, v140, v144
	global_store_dwordx4 v14, v[40:43], s[2:3] offset:16
	v_cvt_pk_bf16_f32 v20, v157, v161
	v_cvt_pk_bf16_f32 v21, v165, v169
	v_cvt_pk_bf16_f32 v22, v173, v177
	v_cvt_pk_bf16_f32 v23, v181, v185
	global_store_dwordx4 v15, v[20:23], s[2:3]
	v_cvt_pk_bf16_f32 v24, v189, v193
	v_cvt_pk_bf16_f32 v25, v197, v201
	v_cvt_pk_bf16_f32 v26, v133, v137
	v_cvt_pk_bf16_f32 v27, v141, v145
	global_store_dwordx4 v15, v[24:27], s[2:3] offset:16
	v_cvt_pk_bf16_f32 v28, v204, v208
	v_cvt_pk_bf16_f32 v29, v212, v216
	v_cvt_pk_bf16_f32 v30, v220, v224
	v_cvt_pk_bf16_f32 v31, v228, v232
	global_store_dwordx4 v12, v[28:31], s[6:7]
	v_cvt_pk_bf16_f32 v32, v236, v240
	v_cvt_pk_bf16_f32 v33, v244, v248
	v_cvt_pk_bf16_f32 v34, v50, v54
	v_cvt_pk_bf16_f32 v35, v58, v62
	global_store_dwordx4 v12, v[32:35], s[6:7] offset:16
	v_cvt_pk_bf16_f32 v36, v205, v209
	v_cvt_pk_bf16_f32 v37, v213, v217
	v_cvt_pk_bf16_f32 v38, v221, v225
	v_cvt_pk_bf16_f32 v39, v229, v233
	global_store_dwordx4 v13, v[36:39], s[6:7]
	v_cvt_pk_bf16_f32 v40, v237, v241
	v_cvt_pk_bf16_f32 v41, v245, v249
	v_cvt_pk_bf16_f32 v42, v51, v55
	v_cvt_pk_bf16_f32 v43, v59, v63
	global_store_dwordx4 v13, v[40:43], s[6:7] offset:16
	v_cvt_pk_bf16_f32 v20, v206, v210
	v_cvt_pk_bf16_f32 v21, v214, v218
	v_cvt_pk_bf16_f32 v22, v222, v226
	v_cvt_pk_bf16_f32 v23, v230, v234
	global_store_dwordx4 v14, v[20:23], s[6:7]
	v_cvt_pk_bf16_f32 v24, v238, v242
	v_cvt_pk_bf16_f32 v25, v246, v250
	v_cvt_pk_bf16_f32 v26, v52, v56
	v_cvt_pk_bf16_f32 v27, v60, v64
	global_store_dwordx4 v14, v[24:27], s[6:7] offset:16
	v_cvt_pk_bf16_f32 v28, v207, v211
	v_cvt_pk_bf16_f32 v29, v215, v219
	v_cvt_pk_bf16_f32 v30, v223, v227
	v_cvt_pk_bf16_f32 v31, v231, v235
	global_store_dwordx4 v15, v[28:31], s[6:7]
	v_cvt_pk_bf16_f32 v32, v239, v243
	v_cvt_pk_bf16_f32 v33, v247, v251
	v_cvt_pk_bf16_f32 v34, v53, v57
	v_cvt_pk_bf16_f32 v35, v61, v65
	global_store_dwordx4 v15, v[32:35], s[6:7] offset:16
	s_waitcnt vmcnt(16)
	s_branch .Lw2d_loop
